# v_n1 + attention LDS-DMA pieces issued after each exp/cvt block instead of before it
# baseline (speedup 1.0000x reference)
.LBB0_1011:
	s_nop 3
	v_exp_f32_e32 v96, v96
	v_exp_f32_e32 v97, v97
	v_exp_f32_e32 v98, v98
	v_exp_f32_e32 v99, v99
	v_exp_f32_e32 v100, v100
	v_exp_f32_e32 v101, v101
	v_exp_f32_e32 v102, v102
	v_exp_f32_e32 v103, v103
	v_cvt_pk_bf16_f32 v216, v96, v97
	v_cvt_pk_bf16_f32 v217, v98, v99
	v_cvt_pk_bf16_f32 v218, v100, v101
	v_cvt_pk_bf16_f32 v219, v102, v103
	s_cbranch_scc1 .Latt_dma0
	s_add_i32 s6, s86, s63
	s_mov_b32 s7, m0
	s_mov_b32 m0, s6
	s_nop 0
	global_load_lds_dwordx4 v211, s[48:49]
	s_mov_b32 m0, s7
.Latt_dma0:
	ds_read_b64_tr_b16 v[152:153], v156 offset:17408
	ds_read_b64_tr_b16 v[154:155], v156 offset:17920
	ds_read_b64_tr_b16 v[148:149], v156 offset:21504
	ds_read_b64_tr_b16 v[150:151], v156 offset:22016
	ds_read_b64_tr_b16 v[100:101], v156 offset:25600
	ds_read_b64_tr_b16 v[102:103], v156 offset:26112
	ds_read_b64_tr_b16 v[96:97], v156 offset:29696
	ds_read_b64_tr_b16 v[98:99], v156 offset:30208
	s_waitcnt lgkmcnt(14)
	v_mfma_f32_32x32x16_bf16 v[48:63], v[216:219], v[144:147], v[48:63]
	s_andn2_b64 vcc, exec, s[50:51]
	s_waitcnt lgkmcnt(12)
	v_mfma_f32_32x32x16_bf16 v[32:47], v[216:219], v[140:143], v[32:47]
	s_waitcnt lgkmcnt(10)
	v_mfma_f32_32x32x16_bf16 v[16:31], v[216:219], v[136:139], v[16:31]
	s_waitcnt lgkmcnt(8)
	v_mfma_f32_32x32x16_bf16 v[0:15], v[216:219], v[132:135], v[0:15]
	v_cndmask_b32_e64 v132, 0, 1, s[50:51]
	v_cmp_ne_u32_e64 s[6:7], 1, v132
	v_mfma_f32_32x32x16_bf16 v[64:79], v[216:219], v[128:131], v[64:79]
.LBB0_1013:
	v_exp_f32_e32 v104, v104
	v_exp_f32_e32 v105, v105
	v_exp_f32_e32 v106, v106
	v_exp_f32_e32 v107, v107
	v_exp_f32_e32 v108, v108
	v_exp_f32_e32 v109, v109
	v_exp_f32_e32 v110, v110
	v_exp_f32_e32 v111, v111
	v_cvt_pk_bf16_f32 v140, v104, v105
	v_cvt_pk_bf16_f32 v141, v106, v107
	v_cvt_pk_bf16_f32 v142, v108, v109
	v_cvt_pk_bf16_f32 v143, v110, v111
	s_cbranch_vccnz .Latt_dma1
	s_add_u32 s50, s42, 0x80
	s_addc_u32 s51, s43, 0
	s_add_i32 s58, s86, s63
	s_addk_i32 s58, 0x2000
	s_mov_b32 s59, m0
	s_mov_b32 m0, s58
	s_nop 0
	global_load_lds_dwordx4 v211, s[50:51]
	s_mov_b32 m0, s59
.Latt_dma1:
	ds_read_b64_tr_b16 v[136:137], v156 offset:18432
	ds_read_b64_tr_b16 v[138:139], v156 offset:18944
	ds_read_b64_tr_b16 v[132:133], v156 offset:22528
	ds_read_b64_tr_b16 v[134:135], v156 offset:23040
	ds_read_b64_tr_b16 v[108:109], v156 offset:26624
	ds_read_b64_tr_b16 v[110:111], v156 offset:27136
	ds_read_b64_tr_b16 v[104:105], v156 offset:30720
	ds_read_b64_tr_b16 v[106:107], v156 offset:31232
	s_waitcnt lgkmcnt(14)
	v_mfma_f32_32x32x16_bf16 v[48:63], v[140:143], v[152:155], v[48:63]
	s_and_b64 vcc, exec, s[6:7]
	s_waitcnt lgkmcnt(12)
	v_mfma_f32_32x32x16_bf16 v[32:47], v[140:143], v[148:151], v[32:47]
	s_waitcnt lgkmcnt(10)
	v_mfma_f32_32x32x16_bf16 v[16:31], v[140:143], v[100:103], v[16:31]
	s_waitcnt lgkmcnt(8)
	v_mfma_f32_32x32x16_bf16 v[0:15], v[140:143], v[96:99], v[0:15]
	v_mfma_f32_32x32x16_bf16 v[64:79], v[140:143], v[128:131], v[64:79]
.LBB0_1015:
	v_exp_f32_e32 v80, v80
	v_exp_f32_e32 v81, v81
	v_exp_f32_e32 v82, v82
	v_exp_f32_e32 v83, v83
	v_exp_f32_e32 v84, v84
	v_exp_f32_e32 v85, v85
	v_exp_f32_e32 v86, v86
	v_exp_f32_e32 v87, v87
	v_cvt_pk_bf16_f32 v140, v80, v81
	v_cvt_pk_bf16_f32 v141, v82, v83
	v_cvt_pk_bf16_f32 v142, v84, v85
	v_cvt_pk_bf16_f32 v143, v86, v87
	s_cbranch_vccnz .Latt_dma2
	s_add_i32 s50, s86, s68
	s_mov_b32 s51, m0
	s_mov_b32 m0, s50
	s_nop 0
	global_load_lds_dwordx4 v212, s[40:41]
	s_mov_b32 m0, s51
.Latt_dma2:
	ds_read_b64_tr_b16 v[100:101], v156 offset:19456
	ds_read_b64_tr_b16 v[102:103], v156 offset:19968
	ds_read_b64_tr_b16 v[96:97], v156 offset:23552
	ds_read_b64_tr_b16 v[98:99], v156 offset:24064
	ds_read_b64_tr_b16 v[84:85], v156 offset:27648
	ds_read_b64_tr_b16 v[86:87], v156 offset:28160
	ds_read_b64_tr_b16 v[80:81], v156 offset:31744
	ds_read_b64_tr_b16 v[82:83], v156 offset:32256
	s_waitcnt lgkmcnt(14)
	v_mfma_f32_32x32x16_bf16 v[48:63], v[140:143], v[136:139], v[48:63]
	s_and_b64 vcc, exec, s[6:7]
	s_waitcnt lgkmcnt(12)
	v_mfma_f32_32x32x16_bf16 v[32:47], v[140:143], v[132:135], v[32:47]
	s_waitcnt lgkmcnt(10)
	v_mfma_f32_32x32x16_bf16 v[16:31], v[140:143], v[108:111], v[16:31]
	s_waitcnt lgkmcnt(8)
	v_mfma_f32_32x32x16_bf16 v[0:15], v[140:143], v[104:107], v[0:15]
	v_mfma_f32_32x32x16_bf16 v[64:79], v[140:143], v[128:131], v[64:79]
	s_cbranch_vccnz .LBB0_1004
	s_add_u32 s6, s42, 0x480
	s_addc_u32 s7, s43, 0
	s_add_i32 s50, s86, s68
	s_addk_i32 s50, 0x2000
	s_mov_b32 s51, m0
	s_mov_b32 m0, s50
	s_nop 0
	global_load_lds_dwordx4 v212, s[6:7]
	s_mov_b32 m0, s51
	s_branch .LBB0_1004
